# v23: v18 + next-tile coordinates by shift/mask instead of generic division (group size is always 8) + layer-B projection epilogue issues its row loads before the slab-address arithmetic
# speedup vs baseline: 1.0086x; 1.0035x over previous
.LBB0_153:
	s_add_i32 s47, s47, 1
	s_mul_i32 s3, s47, s67
	s_mul_hi_u32 s4, s47, s64
	s_add_i32 s4, s4, s3
	s_mul_i32 s3, s47, s64
	s_add_u32 s8, s3, s76
	s_addc_u32 s9, s4, s66
	v_mov_b64_e32 v[4:5], 0xa00
	v_cmp_lt_i64_e64 s[4:5], s[8:9], v[4:5]
	v_mov_b64_e32 v[4:5], 0x9ff
	v_cmp_gt_i64_e32 vcc, s[8:9], v[4:5]
	s_cbranch_vccnz .LBB0_155
	s_ashr_i32 s3, s8, 31
	s_lshr_b32 s3, s3, 29
	s_add_i32 s3, s8, s3
	s_ashr_i32 s9, s3, 3
	s_and_b32 s3, s3, -8
	s_sub_i32 s3, s8, s3
	s_cmp_lt_i32 s3, 0
	s_cselect_b32 s8, s70, 0x140
	s_mul_i32 s3, s3, s8
	s_add_i32 s3, s3, s9
	s_mul_hi_i32 s8, s3, 0x66666667
	s_lshr_b32 s9, s8, 31
	s_ashr_i32 s8, s8, 7
	s_add_i32 s8, s8, s9
	s_lshl_b32 s9, s8, 3
	s_mulk_i32 s8, 0x140
	s_sub_i32 s3, s3, s8
	s_lshr_b32 s20, s3, 3
	s_and_b32 s3, s3, 7
	s_add_i32 s22, s9, s3

.LBB0_163:
	v_lshlrev_b32_e32 v153, 2, v152
	global_load_dword v180, v153, s[16:17]
	global_load_dword v181, v153, s[16:17] offset:64
	global_load_dword v182, v153, s[16:17] offset:128
	global_load_dword v183, v153, s[16:17] offset:192
	global_load_dword v184, v153, s[16:17] offset:512
	global_load_dword v185, v153, s[16:17] offset:576
	global_load_dword v186, v153, s[16:17] offset:640
	global_load_dword v187, v153, s[16:17] offset:704
	s_mul_hi_i32 s6, s48, 0x2aaaaaab
	s_lshr_b32 s7, s6, 31
	s_ashr_i32 s6, s6, 1
	s_add_i32 s9, s6, s7
	s_mul_i32 s6, s9, 12
	s_sub_i32 s6, s48, s6
	s_ashr_i32 s21, s6, 2
	s_sub_u32 s0, s41, 0x4d00000
	s_subb_u32 s1, s43, 0
	s_add_u32 s2, s0, 0x200000
	s_addc_u32 s3, s1, 0
	s_cmp_gt_i32 s21, 1
	s_cbranch_scc1 .Lb1q_vonly
	v_subrev_u32_e32 v154, s0, v144
	v_lshl_add_u32 v155, v152, 7, v154
	v_add_u32_e32 v156, 0x1000, v155
	global_load_dwordx4 v[188:191], v155, s[0:1]
	global_load_dwordx4 v[192:195], v155, s[2:3]
	global_load_dwordx4 v[196:199], v155, s[0:1] offset:2048
	global_load_dwordx4 v[200:203], v155, s[2:3] offset:2048
	global_load_dwordx4 v[204:207], v156, s[0:1]
	global_load_dwordx4 v[208:211], v156, s[2:3]
	global_load_dwordx4 v[212:215], v156, s[0:1] offset:2048
	global_load_dwordx4 v[216:219], v156, s[2:3] offset:2048
	s_lshl_b32 s23, s48, 2
	s_and_b32 s23, s23, 12
	s_or_b32 s23, s23, s46
	s_lshl_b32 s28, s9, 1
	s_sub_i32 s29, 14, s28
	s_cmp_eq_u32 s21, 2
	s_cselect_b32 s7, 1, 0
	s_or_b32 s7, s28, s7
	s_cmp_eq_u32 s21, 0
	s_cselect_b32 s6, s9, s7
	s_cselect_b32 s8, 0, 0x6000000
	s_cselect_b32 s7, 0x3e38aa3b, 1.0
	v_mov_b32_e32 v179, s7
	s_add_u32 s8, s41, s8
	s_addc_u32 s9, s43, 0
	s_mov_b32 s7, 0
	s_lshl_b64 s[6:7], s[6:7], 25
	s_add_u32 s6, s8, s6
	s_addc_u32 s7, s9, s7
	s_lshl_b32 s8, s23, 21
	s_add_u32 s6, s6, s8
	s_addc_u32 s7, s7, 0
	s_add_u32 s8, s6, 0x400000
	s_addc_u32 s9, s7, 0
	v_lshlrev_b32_e32 v151, s29, v152
	v_and_b32_e32 v151, 0x3fff, v151
	v_lshrrev_b32_e32 v159, s28, v152
	v_add_u32_e32 v151, v151, v159
	v_lshl_add_u32 v160, v151, 7, v150
	s_lshr_b32 s21, 0x800, s28
	s_lshr_b32 s23, 0x4000, s28
	v_add_u32_e32 v161, s21, v160
	v_add_u32_e32 v162, s21, v161
	v_add_u32_e32 v163, s21, v162
	v_add_u32_e32 v164, s23, v160
	v_add_u32_e32 v165, s21, v164
	v_add_u32_e32 v166, s21, v165
	v_add_u32_e32 v167, s21, v166
	v_add_u32_e32 v157, 0x4000, v155
	v_add_u32_e32 v158, 0x5000, v155
	s_waitcnt vmcnt(6)
	v_mul_f32_e32 v220, v179, v180
	v_pk_mul_f32 v[188:189], v[220:221], v[188:189] op_sel_hi:[0,1]
	v_pk_mul_f32 v[190:191], v[220:221], v[190:191] op_sel_hi:[0,1]
	v_pk_mul_f32 v[192:193], v[220:221], v[192:193] op_sel_hi:[0,1]
	v_pk_mul_f32 v[194:195], v[220:221], v[194:195] op_sel_hi:[0,1]
	v_pk_mul_f32 v[132:133], v[128:129], v[188:189]
	v_pk_mul_f32 v[134:135], v[130:131], v[190:191]
	v_pk_mul_f32 v[224:225], v[124:125], v[188:189]
	v_pk_mul_f32 v[226:227], v[126:127], v[190:191]
	v_pk_fma_f32 v[132:133], v[124:125], v[192:193], v[132:133] neg_lo:[1,0,0] neg_hi:[1,0,0]
	v_pk_fma_f32 v[134:135], v[126:127], v[194:195], v[134:135] neg_lo:[1,0,0] neg_hi:[1,0,0]
	v_pk_fma_f32 v[224:225], v[128:129], v[192:193], v[224:225]
	v_pk_fma_f32 v[226:227], v[130:131], v[194:195], v[226:227]
	v_cvt_pk_bf16_f32 v128, v132, v133
	v_cvt_pk_bf16_f32 v129, v134, v135
	v_cvt_pk_bf16_f32 v130, v224, v225
	v_cvt_pk_bf16_f32 v131, v226, v227
	global_store_dwordx4 v160, v[128:131], s[6:7]
	v_pk_mul_f32 v[168:169], v[120:121], v[188:189]
	v_pk_mul_f32 v[170:171], v[122:123], v[190:191]
	v_pk_mul_f32 v[172:173], v[116:117], v[188:189]
	v_pk_mul_f32 v[174:175], v[118:119], v[190:191]
	v_pk_fma_f32 v[168:169], v[116:117], v[192:193], v[168:169] neg_lo:[1,0,0] neg_hi:[1,0,0]
	v_pk_fma_f32 v[170:171], v[118:119], v[194:195], v[170:171] neg_lo:[1,0,0] neg_hi:[1,0,0]
	v_pk_fma_f32 v[172:173], v[120:121], v[192:193], v[172:173]
	v_pk_fma_f32 v[174:175], v[122:123], v[194:195], v[174:175]
	v_cvt_pk_bf16_f32 v120, v168, v169
	v_cvt_pk_bf16_f32 v121, v170, v171
	v_cvt_pk_bf16_f32 v122, v172, v173
	v_cvt_pk_bf16_f32 v123, v174, v175
	global_store_dwordx4 v160, v[120:123], s[8:9]
	s_waitcnt vmcnt(6)
	v_mul_f32_e32 v220, v179, v181
	v_pk_mul_f32 v[196:197], v[220:221], v[196:197] op_sel_hi:[0,1]
	v_pk_mul_f32 v[198:199], v[220:221], v[198:199] op_sel_hi:[0,1]
	v_pk_mul_f32 v[200:201], v[220:221], v[200:201] op_sel_hi:[0,1]
	v_pk_mul_f32 v[202:203], v[220:221], v[202:203] op_sel_hi:[0,1]
	v_pk_mul_f32 v[132:133], v[112:113], v[196:197]
	v_pk_mul_f32 v[134:135], v[114:115], v[198:199]
	v_pk_mul_f32 v[224:225], v[108:109], v[196:197]
	v_pk_mul_f32 v[226:227], v[110:111], v[198:199]
	v_pk_fma_f32 v[132:133], v[108:109], v[200:201], v[132:133] neg_lo:[1,0,0] neg_hi:[1,0,0]
	v_pk_fma_f32 v[134:135], v[110:111], v[202:203], v[134:135] neg_lo:[1,0,0] neg_hi:[1,0,0]
	v_pk_fma_f32 v[224:225], v[112:113], v[200:201], v[224:225]
	v_pk_fma_f32 v[226:227], v[114:115], v[202:203], v[226:227]
	v_cvt_pk_bf16_f32 v112, v132, v133
	v_cvt_pk_bf16_f32 v113, v134, v135
	v_cvt_pk_bf16_f32 v114, v224, v225
	v_cvt_pk_bf16_f32 v115, v226, v227
	global_store_dwordx4 v161, v[112:115], s[6:7]
	v_pk_mul_f32 v[168:169], v[104:105], v[196:197]
	v_pk_mul_f32 v[170:171], v[106:107], v[198:199]
	v_pk_mul_f32 v[172:173], v[100:101], v[196:197]
	v_pk_mul_f32 v[174:175], v[102:103], v[198:199]
	v_pk_fma_f32 v[168:169], v[100:101], v[200:201], v[168:169] neg_lo:[1,0,0] neg_hi:[1,0,0]
	v_pk_fma_f32 v[170:171], v[102:103], v[202:203], v[170:171] neg_lo:[1,0,0] neg_hi:[1,0,0]
	v_pk_fma_f32 v[172:173], v[104:105], v[200:201], v[172:173]
	v_pk_fma_f32 v[174:175], v[106:107], v[202:203], v[174:175]
	v_cvt_pk_bf16_f32 v104, v168, v169
	v_cvt_pk_bf16_f32 v105, v170, v171
	v_cvt_pk_bf16_f32 v106, v172, v173
	v_cvt_pk_bf16_f32 v107, v174, v175
	global_store_dwordx4 v161, v[104:107], s[8:9]
	global_load_dwordx4 v[100:103], v157, s[0:1]
	global_load_dwordx4 v[104:107], v157, s[2:3]
	global_load_dwordx4 v[108:111], v157, s[0:1] offset:2048
	global_load_dwordx4 v[112:115], v157, s[2:3] offset:2048
	global_load_dwordx4 v[116:119], v158, s[0:1]
	global_load_dwordx4 v[120:123], v158, s[2:3]
	global_load_dwordx4 v[124:127], v158, s[0:1] offset:2048
	global_load_dwordx4 v[128:131], v158, s[2:3] offset:2048
	s_waitcnt vmcnt(14)
	v_mul_f32_e32 v220, v179, v182
	v_pk_mul_f32 v[204:205], v[220:221], v[204:205] op_sel_hi:[0,1]
	v_pk_mul_f32 v[206:207], v[220:221], v[206:207] op_sel_hi:[0,1]
	v_pk_mul_f32 v[208:209], v[220:221], v[208:209] op_sel_hi:[0,1]
	v_pk_mul_f32 v[210:211], v[220:221], v[210:211] op_sel_hi:[0,1]
	v_pk_mul_f32 v[132:133], v[96:97], v[204:205]
	v_pk_mul_f32 v[134:135], v[98:99], v[206:207]
	v_pk_mul_f32 v[224:225], v[92:93], v[204:205]
	v_pk_mul_f32 v[226:227], v[94:95], v[206:207]
	v_pk_fma_f32 v[132:133], v[92:93], v[208:209], v[132:133] neg_lo:[1,0,0] neg_hi:[1,0,0]
	v_pk_fma_f32 v[134:135], v[94:95], v[210:211], v[134:135] neg_lo:[1,0,0] neg_hi:[1,0,0]
	v_pk_fma_f32 v[224:225], v[96:97], v[208:209], v[224:225]
	v_pk_fma_f32 v[226:227], v[98:99], v[210:211], v[226:227]
	v_cvt_pk_bf16_f32 v96, v132, v133
	v_cvt_pk_bf16_f32 v97, v134, v135
	v_cvt_pk_bf16_f32 v98, v224, v225
	v_cvt_pk_bf16_f32 v99, v226, v227
	global_store_dwordx4 v162, v[96:99], s[6:7]
	v_pk_mul_f32 v[168:169], v[88:89], v[204:205]
	v_pk_mul_f32 v[170:171], v[90:91], v[206:207]
	v_pk_mul_f32 v[172:173], v[84:85], v[204:205]
	v_pk_mul_f32 v[174:175], v[86:87], v[206:207]
	v_pk_fma_f32 v[168:169], v[84:85], v[208:209], v[168:169] neg_lo:[1,0,0] neg_hi:[1,0,0]
	v_pk_fma_f32 v[170:171], v[86:87], v[210:211], v[170:171] neg_lo:[1,0,0] neg_hi:[1,0,0]
	v_pk_fma_f32 v[172:173], v[88:89], v[208:209], v[172:173]
	v_pk_fma_f32 v[174:175], v[90:91], v[210:211], v[174:175]
	v_cvt_pk_bf16_f32 v88, v168, v169
	v_cvt_pk_bf16_f32 v89, v170, v171
	v_cvt_pk_bf16_f32 v90, v172, v173
	v_cvt_pk_bf16_f32 v91, v174, v175
	global_store_dwordx4 v162, v[88:91], s[8:9]
	s_waitcnt vmcnt(14)
	v_mul_f32_e32 v220, v179, v183
	v_pk_mul_f32 v[212:213], v[220:221], v[212:213] op_sel_hi:[0,1]
	v_pk_mul_f32 v[214:215], v[220:221], v[214:215] op_sel_hi:[0,1]
	v_pk_mul_f32 v[216:217], v[220:221], v[216:217] op_sel_hi:[0,1]
	v_pk_mul_f32 v[218:219], v[220:221], v[218:219] op_sel_hi:[0,1]
	v_pk_mul_f32 v[132:133], v[80:81], v[212:213]
	v_pk_mul_f32 v[134:135], v[82:83], v[214:215]
	v_pk_mul_f32 v[224:225], v[76:77], v[212:213]
	v_pk_mul_f32 v[226:227], v[78:79], v[214:215]
	v_pk_fma_f32 v[132:133], v[76:77], v[216:217], v[132:133] neg_lo:[1,0,0] neg_hi:[1,0,0]
	v_pk_fma_f32 v[134:135], v[78:79], v[218:219], v[134:135] neg_lo:[1,0,0] neg_hi:[1,0,0]
	v_pk_fma_f32 v[224:225], v[80:81], v[216:217], v[224:225]
	v_pk_fma_f32 v[226:227], v[82:83], v[218:219], v[226:227]
	v_cvt_pk_bf16_f32 v80, v132, v133
	v_cvt_pk_bf16_f32 v81, v134, v135
	v_cvt_pk_bf16_f32 v82, v224, v225
	v_cvt_pk_bf16_f32 v83, v226, v227
	global_store_dwordx4 v163, v[80:83], s[6:7]
	v_pk_mul_f32 v[168:169], v[72:73], v[212:213]
	v_pk_mul_f32 v[170:171], v[74:75], v[214:215]
	v_pk_mul_f32 v[172:173], v[68:69], v[212:213]
	v_pk_mul_f32 v[174:175], v[70:71], v[214:215]
	v_pk_fma_f32 v[168:169], v[68:69], v[216:217], v[168:169] neg_lo:[1,0,0] neg_hi:[1,0,0]
	v_pk_fma_f32 v[170:171], v[70:71], v[218:219], v[170:171] neg_lo:[1,0,0] neg_hi:[1,0,0]
	v_pk_fma_f32 v[172:173], v[72:73], v[216:217], v[172:173]
	v_pk_fma_f32 v[174:175], v[74:75], v[218:219], v[174:175]
	v_cvt_pk_bf16_f32 v72, v168, v169
	v_cvt_pk_bf16_f32 v73, v170, v171
	v_cvt_pk_bf16_f32 v74, v172, v173
	v_cvt_pk_bf16_f32 v75, v174, v175
	global_store_dwordx4 v163, v[72:75], s[8:9]
	s_waitcnt vmcnt(10)
	v_mul_f32_e32 v220, v179, v184
	v_pk_mul_f32 v[100:101], v[220:221], v[100:101] op_sel_hi:[0,1]
	v_pk_mul_f32 v[102:103], v[220:221], v[102:103] op_sel_hi:[0,1]
	v_pk_mul_f32 v[104:105], v[220:221], v[104:105] op_sel_hi:[0,1]
	v_pk_mul_f32 v[106:107], v[220:221], v[106:107] op_sel_hi:[0,1]
	v_pk_mul_f32 v[132:133], v[64:65], v[100:101]
	v_pk_mul_f32 v[134:135], v[66:67], v[102:103]
	v_pk_mul_f32 v[224:225], v[60:61], v[100:101]
	v_pk_mul_f32 v[226:227], v[62:63], v[102:103]
	v_pk_fma_f32 v[132:133], v[60:61], v[104:105], v[132:133] neg_lo:[1,0,0] neg_hi:[1,0,0]
	v_pk_fma_f32 v[134:135], v[62:63], v[106:107], v[134:135] neg_lo:[1,0,0] neg_hi:[1,0,0]
	v_pk_fma_f32 v[224:225], v[64:65], v[104:105], v[224:225]
	v_pk_fma_f32 v[226:227], v[66:67], v[106:107], v[226:227]
	v_cvt_pk_bf16_f32 v64, v132, v133
	v_cvt_pk_bf16_f32 v65, v134, v135
	v_cvt_pk_bf16_f32 v66, v224, v225
	v_cvt_pk_bf16_f32 v67, v226, v227
	global_store_dwordx4 v164, v[64:67], s[6:7]
	v_pk_mul_f32 v[168:169], v[56:57], v[100:101]
	v_pk_mul_f32 v[170:171], v[58:59], v[102:103]
	v_pk_mul_f32 v[172:173], v[52:53], v[100:101]
	v_pk_mul_f32 v[174:175], v[54:55], v[102:103]
	v_pk_fma_f32 v[168:169], v[52:53], v[104:105], v[168:169] neg_lo:[1,0,0] neg_hi:[1,0,0]
	v_pk_fma_f32 v[170:171], v[54:55], v[106:107], v[170:171] neg_lo:[1,0,0] neg_hi:[1,0,0]
	v_pk_fma_f32 v[172:173], v[56:57], v[104:105], v[172:173]
	v_pk_fma_f32 v[174:175], v[58:59], v[106:107], v[174:175]
	v_cvt_pk_bf16_f32 v56, v168, v169
	v_cvt_pk_bf16_f32 v57, v170, v171
	v_cvt_pk_bf16_f32 v58, v172, v173
	v_cvt_pk_bf16_f32 v59, v174, v175
	global_store_dwordx4 v164, v[56:59], s[8:9]
	s_waitcnt vmcnt(10)
	v_mul_f32_e32 v220, v179, v185
	v_pk_mul_f32 v[108:109], v[220:221], v[108:109] op_sel_hi:[0,1]
	v_pk_mul_f32 v[110:111], v[220:221], v[110:111] op_sel_hi:[0,1]
	v_pk_mul_f32 v[112:113], v[220:221], v[112:113] op_sel_hi:[0,1]
	v_pk_mul_f32 v[114:115], v[220:221], v[114:115] op_sel_hi:[0,1]
	v_pk_mul_f32 v[132:133], v[48:49], v[108:109]
	v_pk_mul_f32 v[134:135], v[50:51], v[110:111]
	v_pk_mul_f32 v[224:225], v[44:45], v[108:109]
	v_pk_mul_f32 v[226:227], v[46:47], v[110:111]
	v_pk_fma_f32 v[132:133], v[44:45], v[112:113], v[132:133] neg_lo:[1,0,0] neg_hi:[1,0,0]
	v_pk_fma_f32 v[134:135], v[46:47], v[114:115], v[134:135] neg_lo:[1,0,0] neg_hi:[1,0,0]
	v_pk_fma_f32 v[224:225], v[48:49], v[112:113], v[224:225]
	v_pk_fma_f32 v[226:227], v[50:51], v[114:115], v[226:227]
	v_cvt_pk_bf16_f32 v48, v132, v133
	v_cvt_pk_bf16_f32 v49, v134, v135
	v_cvt_pk_bf16_f32 v50, v224, v225
	v_cvt_pk_bf16_f32 v51, v226, v227
	global_store_dwordx4 v165, v[48:51], s[6:7]
	v_pk_mul_f32 v[168:169], v[40:41], v[108:109]
	v_pk_mul_f32 v[170:171], v[42:43], v[110:111]
	v_pk_mul_f32 v[172:173], v[36:37], v[108:109]
	v_pk_mul_f32 v[174:175], v[38:39], v[110:111]
	v_pk_fma_f32 v[168:169], v[36:37], v[112:113], v[168:169] neg_lo:[1,0,0] neg_hi:[1,0,0]
	v_pk_fma_f32 v[170:171], v[38:39], v[114:115], v[170:171] neg_lo:[1,0,0] neg_hi:[1,0,0]
	v_pk_fma_f32 v[172:173], v[40:41], v[112:113], v[172:173]
	v_pk_fma_f32 v[174:175], v[42:43], v[114:115], v[174:175]
	v_cvt_pk_bf16_f32 v40, v168, v169
	v_cvt_pk_bf16_f32 v41, v170, v171
	v_cvt_pk_bf16_f32 v42, v172, v173
	v_cvt_pk_bf16_f32 v43, v174, v175
	global_store_dwordx4 v165, v[40:43], s[8:9]
	s_waitcnt vmcnt(10)
	v_mul_f32_e32 v220, v179, v186
	v_pk_mul_f32 v[116:117], v[220:221], v[116:117] op_sel_hi:[0,1]
	v_pk_mul_f32 v[118:119], v[220:221], v[118:119] op_sel_hi:[0,1]
	v_pk_mul_f32 v[120:121], v[220:221], v[120:121] op_sel_hi:[0,1]
	v_pk_mul_f32 v[122:123], v[220:221], v[122:123] op_sel_hi:[0,1]
	v_pk_mul_f32 v[132:133], v[32:33], v[116:117]
	v_pk_mul_f32 v[134:135], v[34:35], v[118:119]
	v_pk_mul_f32 v[224:225], v[28:29], v[116:117]
	v_pk_mul_f32 v[226:227], v[30:31], v[118:119]
	v_pk_fma_f32 v[132:133], v[28:29], v[120:121], v[132:133] neg_lo:[1,0,0] neg_hi:[1,0,0]
	v_pk_fma_f32 v[134:135], v[30:31], v[122:123], v[134:135] neg_lo:[1,0,0] neg_hi:[1,0,0]
	v_pk_fma_f32 v[224:225], v[32:33], v[120:121], v[224:225]
	v_pk_fma_f32 v[226:227], v[34:35], v[122:123], v[226:227]
	v_cvt_pk_bf16_f32 v32, v132, v133
	v_cvt_pk_bf16_f32 v33, v134, v135
	v_cvt_pk_bf16_f32 v34, v224, v225
	v_cvt_pk_bf16_f32 v35, v226, v227
	global_store_dwordx4 v166, v[32:35], s[6:7]
	v_pk_mul_f32 v[168:169], v[24:25], v[116:117]
	v_pk_mul_f32 v[170:171], v[26:27], v[118:119]
	v_pk_mul_f32 v[172:173], v[20:21], v[116:117]
	v_pk_mul_f32 v[174:175], v[22:23], v[118:119]
	v_pk_fma_f32 v[168:169], v[20:21], v[120:121], v[168:169] neg_lo:[1,0,0] neg_hi:[1,0,0]
	v_pk_fma_f32 v[170:171], v[22:23], v[122:123], v[170:171] neg_lo:[1,0,0] neg_hi:[1,0,0]
	v_pk_fma_f32 v[172:173], v[24:25], v[120:121], v[172:173]
	v_pk_fma_f32 v[174:175], v[26:27], v[122:123], v[174:175]
	v_cvt_pk_bf16_f32 v24, v168, v169
	v_cvt_pk_bf16_f32 v25, v170, v171
	v_cvt_pk_bf16_f32 v26, v172, v173
	v_cvt_pk_bf16_f32 v27, v174, v175
	global_store_dwordx4 v166, v[24:27], s[8:9]
	s_waitcnt vmcnt(10)
	v_mul_f32_e32 v220, v179, v187
	v_pk_mul_f32 v[124:125], v[220:221], v[124:125] op_sel_hi:[0,1]
	v_pk_mul_f32 v[126:127], v[220:221], v[126:127] op_sel_hi:[0,1]
	v_pk_mul_f32 v[128:129], v[220:221], v[128:129] op_sel_hi:[0,1]
	v_pk_mul_f32 v[130:131], v[220:221], v[130:131] op_sel_hi:[0,1]
	v_pk_mul_f32 v[132:133], v[16:17], v[124:125]
	v_pk_mul_f32 v[134:135], v[18:19], v[126:127]
	v_pk_mul_f32 v[224:225], v[12:13], v[124:125]
	v_pk_mul_f32 v[226:227], v[14:15], v[126:127]
	v_pk_fma_f32 v[132:133], v[12:13], v[128:129], v[132:133] neg_lo:[1,0,0] neg_hi:[1,0,0]
	v_pk_fma_f32 v[134:135], v[14:15], v[130:131], v[134:135] neg_lo:[1,0,0] neg_hi:[1,0,0]
	v_pk_fma_f32 v[224:225], v[16:17], v[128:129], v[224:225]
	v_pk_fma_f32 v[226:227], v[18:19], v[130:131], v[226:227]
	v_cvt_pk_bf16_f32 v16, v132, v133
	v_cvt_pk_bf16_f32 v17, v134, v135
	v_cvt_pk_bf16_f32 v18, v224, v225
	v_cvt_pk_bf16_f32 v19, v226, v227
	global_store_dwordx4 v167, v[16:19], s[6:7]
	v_pk_mul_f32 v[168:169], v[8:9], v[124:125]
	v_pk_mul_f32 v[170:171], v[10:11], v[126:127]
	v_pk_mul_f32 v[172:173], v[4:5], v[124:125]
	v_pk_mul_f32 v[174:175], v[6:7], v[126:127]
	v_pk_fma_f32 v[168:169], v[4:5], v[128:129], v[168:169] neg_lo:[1,0,0] neg_hi:[1,0,0]
	v_pk_fma_f32 v[170:171], v[6:7], v[130:131], v[170:171] neg_lo:[1,0,0] neg_hi:[1,0,0]
	v_pk_fma_f32 v[172:173], v[8:9], v[128:129], v[172:173]
	v_pk_fma_f32 v[174:175], v[10:11], v[130:131], v[174:175]
	v_cvt_pk_bf16_f32 v8, v168, v169
	v_cvt_pk_bf16_f32 v9, v170, v171
	v_cvt_pk_bf16_f32 v10, v172, v173
	v_cvt_pk_bf16_f32 v11, v174, v175
	global_store_dwordx4 v167, v[8:11], s[8:9]
	s_branch .Lb1q_done
.Lb1q_vonly:
	s_lshl_b32 s23, s48, 2
	s_and_b32 s23, s23, 12
	s_or_b32 s23, s23, s46
	s_lshl_b32 s28, s9, 1
	s_sub_i32 s29, 14, s28
	s_cmp_eq_u32 s21, 2
	s_cselect_b32 s7, 1, 0
	s_or_b32 s7, s28, s7
	s_cmp_eq_u32 s21, 0
	s_cselect_b32 s6, s9, s7
	s_cselect_b32 s8, 0, 0x6000000
	s_cselect_b32 s7, 0x3e38aa3b, 1.0
	v_mov_b32_e32 v179, s7
	s_add_u32 s8, s41, s8
	s_addc_u32 s9, s43, 0
	s_mov_b32 s7, 0
	s_lshl_b64 s[6:7], s[6:7], 25
	s_add_u32 s6, s8, s6
	s_addc_u32 s7, s9, s7
	s_lshl_b32 s8, s23, 21
	s_add_u32 s6, s6, s8
	s_addc_u32 s7, s7, 0
	s_add_u32 s8, s6, 0x400000
	s_addc_u32 s9, s7, 0
	v_lshlrev_b32_e32 v151, s29, v152
	v_and_b32_e32 v151, 0x3fff, v151
	v_lshrrev_b32_e32 v159, s28, v152
	v_add_u32_e32 v151, v151, v159
	v_lshl_add_u32 v160, v151, 7, v150
	s_lshr_b32 s21, 0x800, s28
	s_lshr_b32 s23, 0x4000, s28
	v_add_u32_e32 v161, s21, v160
	v_add_u32_e32 v162, s21, v161
	v_add_u32_e32 v163, s21, v162
	v_add_u32_e32 v164, s23, v160
	v_add_u32_e32 v165, s21, v164
	v_add_u32_e32 v166, s21, v165
	v_add_u32_e32 v167, s21, v166
	s_waitcnt vmcnt(7)
	v_mul_f32_e32 v220, v179, v180
	v_pk_mul_f32 v[128:129], v[128:129], v[220:221] op_sel_hi:[1,0]
	v_pk_mul_f32 v[130:131], v[130:131], v[220:221] op_sel_hi:[1,0]
	v_pk_mul_f32 v[124:125], v[124:125], v[220:221] op_sel_hi:[1,0]
	v_pk_mul_f32 v[126:127], v[126:127], v[220:221] op_sel_hi:[1,0]
	v_cvt_pk_bf16_f32 v128, v128, v129
	v_cvt_pk_bf16_f32 v129, v130, v131
	v_cvt_pk_bf16_f32 v130, v124, v125
	v_cvt_pk_bf16_f32 v131, v126, v127
	global_store_dwordx4 v160, v[128:131], s[6:7]
	v_pk_mul_f32 v[120:121], v[120:121], v[220:221] op_sel_hi:[1,0]
	v_pk_mul_f32 v[122:123], v[122:123], v[220:221] op_sel_hi:[1,0]
	v_pk_mul_f32 v[116:117], v[116:117], v[220:221] op_sel_hi:[1,0]
	v_pk_mul_f32 v[118:119], v[118:119], v[220:221] op_sel_hi:[1,0]
	v_cvt_pk_bf16_f32 v120, v120, v121
	v_cvt_pk_bf16_f32 v121, v122, v123
	v_cvt_pk_bf16_f32 v122, v116, v117
	v_cvt_pk_bf16_f32 v123, v118, v119
	global_store_dwordx4 v160, v[120:123], s[8:9]
	s_waitcnt vmcnt(8)
	v_mul_f32_e32 v220, v179, v181
	v_pk_mul_f32 v[112:113], v[112:113], v[220:221] op_sel_hi:[1,0]
	v_pk_mul_f32 v[114:115], v[114:115], v[220:221] op_sel_hi:[1,0]
	v_pk_mul_f32 v[108:109], v[108:109], v[220:221] op_sel_hi:[1,0]
	v_pk_mul_f32 v[110:111], v[110:111], v[220:221] op_sel_hi:[1,0]
	v_cvt_pk_bf16_f32 v112, v112, v113
	v_cvt_pk_bf16_f32 v113, v114, v115
	v_cvt_pk_bf16_f32 v114, v108, v109
	v_cvt_pk_bf16_f32 v115, v110, v111
	global_store_dwordx4 v161, v[112:115], s[6:7]
	v_pk_mul_f32 v[104:105], v[104:105], v[220:221] op_sel_hi:[1,0]
	v_pk_mul_f32 v[106:107], v[106:107], v[220:221] op_sel_hi:[1,0]
	v_pk_mul_f32 v[100:101], v[100:101], v[220:221] op_sel_hi:[1,0]
	v_pk_mul_f32 v[102:103], v[102:103], v[220:221] op_sel_hi:[1,0]
	v_cvt_pk_bf16_f32 v104, v104, v105
	v_cvt_pk_bf16_f32 v105, v106, v107
	v_cvt_pk_bf16_f32 v106, v100, v101
	v_cvt_pk_bf16_f32 v107, v102, v103
	global_store_dwordx4 v161, v[104:107], s[8:9]
	s_waitcnt vmcnt(9)
	v_mul_f32_e32 v220, v179, v182
	v_pk_mul_f32 v[96:97], v[96:97], v[220:221] op_sel_hi:[1,0]
	v_pk_mul_f32 v[98:99], v[98:99], v[220:221] op_sel_hi:[1,0]
	v_pk_mul_f32 v[92:93], v[92:93], v[220:221] op_sel_hi:[1,0]
	v_pk_mul_f32 v[94:95], v[94:95], v[220:221] op_sel_hi:[1,0]
	v_cvt_pk_bf16_f32 v96, v96, v97
	v_cvt_pk_bf16_f32 v97, v98, v99
	v_cvt_pk_bf16_f32 v98, v92, v93
	v_cvt_pk_bf16_f32 v99, v94, v95
	global_store_dwordx4 v162, v[96:99], s[6:7]
	v_pk_mul_f32 v[88:89], v[88:89], v[220:221] op_sel_hi:[1,0]
	v_pk_mul_f32 v[90:91], v[90:91], v[220:221] op_sel_hi:[1,0]
	v_pk_mul_f32 v[84:85], v[84:85], v[220:221] op_sel_hi:[1,0]
	v_pk_mul_f32 v[86:87], v[86:87], v[220:221] op_sel_hi:[1,0]
	v_cvt_pk_bf16_f32 v88, v88, v89
	v_cvt_pk_bf16_f32 v89, v90, v91
	v_cvt_pk_bf16_f32 v90, v84, v85
	v_cvt_pk_bf16_f32 v91, v86, v87
	global_store_dwordx4 v162, v[88:91], s[8:9]
	s_waitcnt vmcnt(10)
	v_mul_f32_e32 v220, v179, v183
	v_pk_mul_f32 v[80:81], v[80:81], v[220:221] op_sel_hi:[1,0]
	v_pk_mul_f32 v[82:83], v[82:83], v[220:221] op_sel_hi:[1,0]
	v_pk_mul_f32 v[76:77], v[76:77], v[220:221] op_sel_hi:[1,0]
	v_pk_mul_f32 v[78:79], v[78:79], v[220:221] op_sel_hi:[1,0]
	v_cvt_pk_bf16_f32 v80, v80, v81
	v_cvt_pk_bf16_f32 v81, v82, v83
	v_cvt_pk_bf16_f32 v82, v76, v77
	v_cvt_pk_bf16_f32 v83, v78, v79
	global_store_dwordx4 v163, v[80:83], s[6:7]
	v_pk_mul_f32 v[72:73], v[72:73], v[220:221] op_sel_hi:[1,0]
	v_pk_mul_f32 v[74:75], v[74:75], v[220:221] op_sel_hi:[1,0]
	v_pk_mul_f32 v[68:69], v[68:69], v[220:221] op_sel_hi:[1,0]
	v_pk_mul_f32 v[70:71], v[70:71], v[220:221] op_sel_hi:[1,0]
	v_cvt_pk_bf16_f32 v72, v72, v73
	v_cvt_pk_bf16_f32 v73, v74, v75
	v_cvt_pk_bf16_f32 v74, v68, v69
	v_cvt_pk_bf16_f32 v75, v70, v71
	global_store_dwordx4 v163, v[72:75], s[8:9]
	s_waitcnt vmcnt(11)
	v_mul_f32_e32 v220, v179, v184
	v_pk_mul_f32 v[64:65], v[64:65], v[220:221] op_sel_hi:[1,0]
	v_pk_mul_f32 v[66:67], v[66:67], v[220:221] op_sel_hi:[1,0]
	v_pk_mul_f32 v[60:61], v[60:61], v[220:221] op_sel_hi:[1,0]
	v_pk_mul_f32 v[62:63], v[62:63], v[220:221] op_sel_hi:[1,0]
	v_cvt_pk_bf16_f32 v64, v64, v65
	v_cvt_pk_bf16_f32 v65, v66, v67
	v_cvt_pk_bf16_f32 v66, v60, v61
	v_cvt_pk_bf16_f32 v67, v62, v63
	global_store_dwordx4 v164, v[64:67], s[6:7]
	v_pk_mul_f32 v[56:57], v[56:57], v[220:221] op_sel_hi:[1,0]
	v_pk_mul_f32 v[58:59], v[58:59], v[220:221] op_sel_hi:[1,0]
	v_pk_mul_f32 v[52:53], v[52:53], v[220:221] op_sel_hi:[1,0]
	v_pk_mul_f32 v[54:55], v[54:55], v[220:221] op_sel_hi:[1,0]
	v_cvt_pk_bf16_f32 v56, v56, v57
	v_cvt_pk_bf16_f32 v57, v58, v59
	v_cvt_pk_bf16_f32 v58, v52, v53
	v_cvt_pk_bf16_f32 v59, v54, v55
	global_store_dwordx4 v164, v[56:59], s[8:9]
	s_waitcnt vmcnt(12)
	v_mul_f32_e32 v220, v179, v185
	v_pk_mul_f32 v[48:49], v[48:49], v[220:221] op_sel_hi:[1,0]
	v_pk_mul_f32 v[50:51], v[50:51], v[220:221] op_sel_hi:[1,0]
	v_pk_mul_f32 v[44:45], v[44:45], v[220:221] op_sel_hi:[1,0]
	v_pk_mul_f32 v[46:47], v[46:47], v[220:221] op_sel_hi:[1,0]
	v_cvt_pk_bf16_f32 v48, v48, v49
	v_cvt_pk_bf16_f32 v49, v50, v51
	v_cvt_pk_bf16_f32 v50, v44, v45
	v_cvt_pk_bf16_f32 v51, v46, v47
	global_store_dwordx4 v165, v[48:51], s[6:7]
	v_pk_mul_f32 v[40:41], v[40:41], v[220:221] op_sel_hi:[1,0]
	v_pk_mul_f32 v[42:43], v[42:43], v[220:221] op_sel_hi:[1,0]
	v_pk_mul_f32 v[36:37], v[36:37], v[220:221] op_sel_hi:[1,0]
	v_pk_mul_f32 v[38:39], v[38:39], v[220:221] op_sel_hi:[1,0]
	v_cvt_pk_bf16_f32 v40, v40, v41
	v_cvt_pk_bf16_f32 v41, v42, v43
	v_cvt_pk_bf16_f32 v42, v36, v37
	v_cvt_pk_bf16_f32 v43, v38, v39
	global_store_dwordx4 v165, v[40:43], s[8:9]
	s_waitcnt vmcnt(13)
	v_mul_f32_e32 v220, v179, v186
	v_pk_mul_f32 v[32:33], v[32:33], v[220:221] op_sel_hi:[1,0]
	v_pk_mul_f32 v[34:35], v[34:35], v[220:221] op_sel_hi:[1,0]
	v_pk_mul_f32 v[28:29], v[28:29], v[220:221] op_sel_hi:[1,0]
	v_pk_mul_f32 v[30:31], v[30:31], v[220:221] op_sel_hi:[1,0]
	v_cvt_pk_bf16_f32 v32, v32, v33
	v_cvt_pk_bf16_f32 v33, v34, v35
	v_cvt_pk_bf16_f32 v34, v28, v29
	v_cvt_pk_bf16_f32 v35, v30, v31
	global_store_dwordx4 v166, v[32:35], s[6:7]
	v_pk_mul_f32 v[24:25], v[24:25], v[220:221] op_sel_hi:[1,0]
	v_pk_mul_f32 v[26:27], v[26:27], v[220:221] op_sel_hi:[1,0]
	v_pk_mul_f32 v[20:21], v[20:21], v[220:221] op_sel_hi:[1,0]
	v_pk_mul_f32 v[22:23], v[22:23], v[220:221] op_sel_hi:[1,0]
	v_cvt_pk_bf16_f32 v24, v24, v25
	v_cvt_pk_bf16_f32 v25, v26, v27
	v_cvt_pk_bf16_f32 v26, v20, v21
	v_cvt_pk_bf16_f32 v27, v22, v23
	global_store_dwordx4 v166, v[24:27], s[8:9]
	s_waitcnt vmcnt(14)
	v_mul_f32_e32 v220, v179, v187
	v_pk_mul_f32 v[16:17], v[16:17], v[220:221] op_sel_hi:[1,0]
	v_pk_mul_f32 v[18:19], v[18:19], v[220:221] op_sel_hi:[1,0]
	v_pk_mul_f32 v[12:13], v[12:13], v[220:221] op_sel_hi:[1,0]
	v_pk_mul_f32 v[14:15], v[14:15], v[220:221] op_sel_hi:[1,0]
	v_cvt_pk_bf16_f32 v16, v16, v17
	v_cvt_pk_bf16_f32 v17, v18, v19
	v_cvt_pk_bf16_f32 v18, v12, v13
	v_cvt_pk_bf16_f32 v19, v14, v15
	global_store_dwordx4 v167, v[16:19], s[6:7]
	v_pk_mul_f32 v[8:9], v[8:9], v[220:221] op_sel_hi:[1,0]
	v_pk_mul_f32 v[10:11], v[10:11], v[220:221] op_sel_hi:[1,0]
	v_pk_mul_f32 v[4:5], v[4:5], v[220:221] op_sel_hi:[1,0]
	v_pk_mul_f32 v[6:7], v[6:7], v[220:221] op_sel_hi:[1,0]
	v_cvt_pk_bf16_f32 v8, v8, v9
	v_cvt_pk_bf16_f32 v9, v10, v11
	v_cvt_pk_bf16_f32 v10, v4, v5
	v_cvt_pk_bf16_f32 v11, v6, v7
	global_store_dwordx4 v167, v[8:11], s[8:9]

.LBB0_443:
	s_add_i32 s46, s46, 1
	s_mul_i32 s3, s46, s67
	s_mul_hi_u32 s6, s46, s64
	s_add_i32 s6, s6, s3
	s_mul_i32 s3, s46, s64
	s_add_u32 s24, s3, s76
	s_addc_u32 s25, s6, s66
	v_mov_b64_e32 v[4:5], 0xc00
	v_cmp_lt_i64_e64 s[6:7], s[24:25], v[4:5]
	v_mov_b64_e32 v[4:5], 0xbff
	v_cmp_gt_i64_e32 vcc, s[24:25], v[4:5]
	s_cbranch_vccnz .LBB0_445
	s_ashr_i32 s3, s24, 31
	s_lshr_b32 s3, s3, 29
	s_add_i32 s3, s24, s3
	s_ashr_i32 s20, s3, 3
	s_and_b32 s3, s3, -8
	s_sub_i32 s3, s24, s3
	s_cmp_lt_i32 s3, 0
	s_movk_i32 s21, 0x181
	s_cselect_b32 s21, s21, 0x180
	s_mul_i32 s3, s3, s21
	s_add_i32 s3, s3, s20
	s_mul_hi_i32 s20, s3, 0x2aaaaaab
	s_lshr_b32 s21, s20, 31
	s_ashr_i32 s20, s20, 5
	s_add_i32 s20, s20, s21
	s_lshl_b32 s21, s20, 3
	s_mulk_i32 s20, 0xc0
	s_sub_i32 s3, s3, s20
	s_lshr_b32 s20, s3, 3
	s_and_b32 s3, s3, 7
	s_add_i32 s22, s21, s3
